# grid barrier: the first local arriver of each round starts the XCD L2 write-back early (on top of v8)
# baseline (speedup 1.0000x reference)
.LBB0_95:
	s_or_b64 exec, exec, s[14:15]
	s_waitcnt lgkmcnt(1)
	v_cvt_f32_u32_e32 v4, v2
	s_waitcnt vmcnt(0)
	v_readfirstlane_b32 s1, v3
	v_sub_u32_e32 v3, 0, v2
	v_rcp_iflag_f32_e32 v4, v4
	v_add_u32_e32 v5, s1, v1
	v_mul_f32_e32 v4, 0x4f7ffffe, v4
	v_cvt_u32_f32_e32 v4, v4
	v_mul_lo_u32 v1, v3, v4
	v_mul_hi_u32 v1, v4, v1
	v_add_u32_e32 v1, v4, v1
	v_mul_hi_u32 v1, v5, v1
	v_mul_lo_u32 v3, v1, v2
	v_sub_u32_e32 v3, v5, v3
	v_add_u32_e32 v4, 1, v1
	v_cmp_ge_u32_e32 vcc, v3, v2
	s_nop 1
	v_cndmask_b32_e32 v1, v1, v4, vcc
	v_sub_u32_e32 v4, v3, v2
	v_cndmask_b32_e32 v3, v3, v4, vcc
	v_add_u32_e32 v4, 1, v1
	v_cmp_ge_u32_e32 vcc, v3, v2
	v_add_u32_e32 v3, 1, v5
	s_nop 0
	v_cndmask_b32_e32 v1, v1, v4, vcc
	v_mul_lo_u32 v4, v2, v1
	v_add_u32_e32 v2, v4, v2
	v_cmp_ne_u32_e32 vcc, v3, v2
	s_and_saveexec_b64 s[2:3], vcc
	s_xor_b64 s[8:9], exec, s[2:3]
	s_cbranch_execz .LBB0_109
	v_cmp_eq_u32_e32 vcc, v5, v4
	s_cbranch_vccz .Lbar_nofirst_0
	buffer_wbl2 sc1
.Lbar_nofirst_0:
	s_add_i32 s2, s0, 0x900
	s_mov_b32 s3, 0
	s_lshl_b64 s[2:3], s[2:3], 2
	s_add_u32 s16, s92, s2
	s_addc_u32 s17, s93, s3
	s_waitcnt lgkmcnt(0)
	v_mov_b32_e32 v0, 0
	buffer_inv sc1
	global_load_dword v2, v0, s[16:17] sc1
	s_waitcnt vmcnt(0)
	v_cmp_eq_u32_e32 vcc, v2, v1
	s_and_saveexec_b64 s[12:13], vcc
	s_cbranch_execz .LBB0_108
	s_add_u32 s14, s10, 0x1ce00200
	s_addc_u32 s15, s11, 0
	s_mov_b32 s1, 1
	s_mov_b64 s[18:19], 0
	s_branch .LBB0_99

.LBB0_381:
	s_or_b64 exec, exec, s[10:11]
	s_waitcnt lgkmcnt(1)
	v_cvt_f32_u32_e32 v5, v3
	s_waitcnt vmcnt(0)
	v_readfirstlane_b32 s8, v4
	v_sub_u32_e32 v4, 0, v3
	v_rcp_iflag_f32_e32 v5, v5
	v_add_u32_e32 v6, s8, v1
	v_mul_f32_e32 v5, 0x4f7ffffe, v5
	v_cvt_u32_f32_e32 v5, v5
	v_mul_lo_u32 v1, v4, v5
	v_mul_hi_u32 v1, v5, v1
	v_add_u32_e32 v1, v5, v1
	v_mul_hi_u32 v1, v6, v1
	v_mul_lo_u32 v4, v1, v3
	v_sub_u32_e32 v4, v6, v4
	v_add_u32_e32 v5, 1, v1
	v_sub_u32_e32 v7, v4, v3
	v_cmp_ge_u32_e32 vcc, v4, v3
	s_nop 1
	v_cndmask_b32_e32 v1, v1, v5, vcc
	v_cndmask_b32_e32 v4, v4, v7, vcc
	v_add_u32_e32 v5, 1, v1
	v_cmp_ge_u32_e32 vcc, v4, v3
	v_add_u32_e32 v4, 1, v6
	s_nop 0
	v_cndmask_b32_e32 v1, v1, v5, vcc
	v_mul_lo_u32 v5, v3, v1
	v_add_u32_e32 v3, v5, v3
	v_cmp_ne_u32_e32 vcc, v4, v3
	s_and_saveexec_b64 s[8:9], vcc
	s_xor_b64 s[8:9], exec, s[8:9]
	s_cbranch_execz .LBB0_395
	v_cmp_eq_u32_e32 vcc, v6, v5
	s_cbranch_vccz .Lbar_nofirst_1
	buffer_wbl2 sc1
.Lbar_nofirst_1:
	s_add_i32 s94, s24, 0x900
	s_lshl_b64 s[10:11], s[94:95], 2
	s_add_u32 s12, s92, s10
	s_addc_u32 s13, s93, s11
	s_waitcnt lgkmcnt(0)
	buffer_inv sc1
	global_load_dword v0, v2, s[12:13] sc1
	s_waitcnt vmcnt(0)
	v_cmp_eq_u32_e32 vcc, v0, v1
	s_and_saveexec_b64 s[10:11], vcc
	s_cbranch_execz .LBB0_394
	s_mov_b32 s25, 1
	s_mov_b64 s[14:15], 0
	s_branch .LBB0_385

.LBB0_436:
	s_or_b64 exec, exec, s[10:11]
	s_waitcnt lgkmcnt(1)
	v_cvt_f32_u32_e32 v5, v3
	s_waitcnt vmcnt(0)
	v_readfirstlane_b32 s8, v4
	v_sub_u32_e32 v4, 0, v3
	v_rcp_iflag_f32_e32 v5, v5
	v_add_u32_e32 v6, s8, v1
	v_mul_f32_e32 v5, 0x4f7ffffe, v5
	v_cvt_u32_f32_e32 v5, v5
	v_mul_lo_u32 v1, v4, v5
	v_mul_hi_u32 v1, v5, v1
	v_add_u32_e32 v1, v5, v1
	v_mul_hi_u32 v1, v6, v1
	v_mul_lo_u32 v4, v1, v3
	v_sub_u32_e32 v4, v6, v4
	v_add_u32_e32 v5, 1, v1
	v_cmp_ge_u32_e32 vcc, v4, v3
	s_nop 1
	v_cndmask_b32_e32 v1, v1, v5, vcc
	v_sub_u32_e32 v5, v4, v3
	v_cndmask_b32_e32 v4, v4, v5, vcc
	v_add_u32_e32 v5, 1, v1
	v_cmp_ge_u32_e32 vcc, v4, v3
	v_add_u32_e32 v4, 1, v6
	s_nop 0
	v_cndmask_b32_e32 v1, v1, v5, vcc
	v_mul_lo_u32 v5, v3, v1
	v_add_u32_e32 v3, v5, v3
	v_cmp_ne_u32_e32 vcc, v4, v3
	s_and_saveexec_b64 s[8:9], vcc
	s_xor_b64 s[8:9], exec, s[8:9]
	s_cbranch_execz .LBB0_450
	v_cmp_eq_u32_e32 vcc, v6, v5
	s_cbranch_vccz .Lbar_nofirst_2
	buffer_wbl2 sc1

.LBB0_631:
	s_or_b64 exec, exec, s[12:13]
	s_waitcnt lgkmcnt(1)
	v_cvt_f32_u32_e32 v5, v3
	s_waitcnt vmcnt(0)
	v_readfirstlane_b32 s7, v4
	v_sub_u32_e32 v4, 0, v3
	v_rcp_iflag_f32_e32 v5, v5
	v_add_u32_e32 v6, s7, v1
	v_mul_f32_e32 v5, 0x4f7ffffe, v5
	v_cvt_u32_f32_e32 v5, v5
	v_mul_lo_u32 v1, v4, v5
	v_mul_hi_u32 v1, v5, v1
	v_add_u32_e32 v1, v5, v1
	v_mul_hi_u32 v1, v6, v1
	v_mul_lo_u32 v4, v1, v3
	v_sub_u32_e32 v4, v6, v4
	v_add_u32_e32 v5, 1, v1
	v_cmp_ge_u32_e32 vcc, v4, v3
	s_nop 1
	v_cndmask_b32_e32 v1, v1, v5, vcc
	v_sub_u32_e32 v5, v4, v3
	v_cndmask_b32_e32 v4, v4, v5, vcc
	v_add_u32_e32 v5, 1, v1
	v_cmp_ge_u32_e32 vcc, v4, v3
	v_add_u32_e32 v4, 1, v6
	s_nop 0
	v_cndmask_b32_e32 v1, v1, v5, vcc
	v_mul_lo_u32 v5, v3, v1
	v_add_u32_e32 v3, v5, v3
	v_cmp_ne_u32_e32 vcc, v4, v3
	s_and_saveexec_b64 s[10:11], vcc
	s_xor_b64 s[10:11], exec, s[10:11]
	s_cbranch_execz .LBB0_645
	v_cmp_eq_u32_e32 vcc, v6, v5
	s_cbranch_vccz .Lbar_nofirst_5
	buffer_wbl2 sc1
.Lbar_nofirst_5:
	s_add_i32 s94, s6, 0x900
	s_lshl_b64 s[12:13], s[94:95], 2
	s_add_u32 s14, s92, s12
	s_addc_u32 s15, s93, s13
	s_waitcnt lgkmcnt(0)
	buffer_inv sc1
	global_load_dword v0, v2, s[14:15] sc1
	s_waitcnt vmcnt(0)
	v_cmp_eq_u32_e32 vcc, v0, v1
	s_and_saveexec_b64 s[12:13], vcc
	s_cbranch_execz .LBB0_644
	s_mov_b32 s7, 1
	s_mov_b64 s[16:17], 0
	s_branch .LBB0_635
